# P0 S5 matrices: TY builder rewritten by hand without the three-way divergence (lag part 4 chunks per wait, C.a^(t+1) part with cre/cim read once)
# speedup vs baseline: 1.0170x; 1.0065x over previous
.LBB0_99:
	s_or_b64 exec, exec, s[4:5]
	v_mov_b32_e32 v5, 0
	s_load_dwordx16 s[12:27], s[0:1], 0x180
	s_mul_i32 s4, s2, 0x30000
	s_mul_hi_u32 s5, s2, 0x30000
	s_mov_b64 s[6:7], 0
	v_mov_b32_e32 v1, v136
	s_waitcnt lgkmcnt(0)
	s_add_u32 s4, s18, s4
	s_addc_u32 s5, s19, s5
	s_barrier
	v_lshrrev_b32_e32 v1, 5, v136
	v_and_b32_e32 v7, 31, v136
	v_lshrrev_b32_e32 v6, 1, v7
	v_and_b32_e32 v4, 1, v7
	v_lshlrev_b32_e32 v4, 5, v4
	v_lshl_add_u32 v4, v1, 6, v4
	v_lshlrev_b32_e32 v5, 10, v6
	v_sub_u32_e32 v4, v4, v5
	v_add_u32_e32 v4, 25088, v4
	v_mul_u32_u24_e32 v2, 0x300, v1
	v_lshl_add_u32 v2, v7, 4, v2
	v_mov_b32_e32 v3, 0
	v_lshl_add_u64 v[2:3], s[4:5], 0, v[2:3]
	s_mov_b32 s10, 0x3000
	s_mov_b32 s11, 0
	ds_read_b128 v[8:11], v4 offset:0
	ds_read_b128 v[12:15], v4 offset:16
	ds_read_b128 v[16:19], v4 offset:1024
	ds_read_b128 v[20:23], v4 offset:1040
	ds_read_b128 v[24:27], v4 offset:2048
	ds_read_b128 v[28:31], v4 offset:2064
	ds_read_b128 v[32:35], v4 offset:3072
	ds_read_b128 v[36:39], v4 offset:3088
	s_waitcnt lgkmcnt(0)
	v_cmp_ge_u32_e32 vcc, 0, v6
	v_cndmask_b32_e32 v8, 0, v8, vcc
	v_cndmask_b32_e32 v9, 0, v9, vcc
	v_cndmask_b32_e32 v10, 0, v10, vcc
	v_cndmask_b32_e32 v11, 0, v11, vcc
	v_cndmask_b32_e32 v12, 0, v12, vcc
	v_cndmask_b32_e32 v13, 0, v13, vcc
	v_cndmask_b32_e32 v14, 0, v14, vcc
	v_cndmask_b32_e32 v15, 0, v15, vcc
	v_cvt_pk_bf16_f32 v8, v8, v9
	v_cvt_pk_bf16_f32 v9, v10, v11
	v_cvt_pk_bf16_f32 v10, v12, v13
	v_cvt_pk_bf16_f32 v11, v14, v15
	global_store_dwordx4 v[2:3], v[8:11], off
	v_lshl_add_u64 v[2:3], v[2:3], 0, s[10:11]
	v_cmp_ge_u32_e32 vcc, 1, v6
	v_cndmask_b32_e32 v16, 0, v16, vcc
	v_cndmask_b32_e32 v17, 0, v17, vcc
	v_cndmask_b32_e32 v18, 0, v18, vcc
	v_cndmask_b32_e32 v19, 0, v19, vcc
	v_cndmask_b32_e32 v20, 0, v20, vcc
	v_cndmask_b32_e32 v21, 0, v21, vcc
	v_cndmask_b32_e32 v22, 0, v22, vcc
	v_cndmask_b32_e32 v23, 0, v23, vcc
	v_cvt_pk_bf16_f32 v16, v16, v17
	v_cvt_pk_bf16_f32 v17, v18, v19
	v_cvt_pk_bf16_f32 v18, v20, v21
	v_cvt_pk_bf16_f32 v19, v22, v23
	global_store_dwordx4 v[2:3], v[16:19], off
	v_lshl_add_u64 v[2:3], v[2:3], 0, s[10:11]
	v_cmp_ge_u32_e32 vcc, 2, v6
	v_cndmask_b32_e32 v24, 0, v24, vcc
	v_cndmask_b32_e32 v25, 0, v25, vcc
	v_cndmask_b32_e32 v26, 0, v26, vcc
	v_cndmask_b32_e32 v27, 0, v27, vcc
	v_cndmask_b32_e32 v28, 0, v28, vcc
	v_cndmask_b32_e32 v29, 0, v29, vcc
	v_cndmask_b32_e32 v30, 0, v30, vcc
	v_cndmask_b32_e32 v31, 0, v31, vcc
	v_cvt_pk_bf16_f32 v24, v24, v25
	v_cvt_pk_bf16_f32 v25, v26, v27
	v_cvt_pk_bf16_f32 v26, v28, v29
	v_cvt_pk_bf16_f32 v27, v30, v31
	global_store_dwordx4 v[2:3], v[24:27], off
	v_lshl_add_u64 v[2:3], v[2:3], 0, s[10:11]
	v_cmp_ge_u32_e32 vcc, 3, v6
	v_cndmask_b32_e32 v32, 0, v32, vcc
	v_cndmask_b32_e32 v33, 0, v33, vcc
	v_cndmask_b32_e32 v34, 0, v34, vcc
	v_cndmask_b32_e32 v35, 0, v35, vcc
	v_cndmask_b32_e32 v36, 0, v36, vcc
	v_cndmask_b32_e32 v37, 0, v37, vcc
	v_cndmask_b32_e32 v38, 0, v38, vcc
	v_cndmask_b32_e32 v39, 0, v39, vcc
	v_cvt_pk_bf16_f32 v32, v32, v33
	v_cvt_pk_bf16_f32 v33, v34, v35
	v_cvt_pk_bf16_f32 v34, v36, v37
	v_cvt_pk_bf16_f32 v35, v38, v39
	global_store_dwordx4 v[2:3], v[32:35], off
	v_lshl_add_u64 v[2:3], v[2:3], 0, s[10:11]
	ds_read_b128 v[8:11], v4 offset:4096
	ds_read_b128 v[12:15], v4 offset:4112
	ds_read_b128 v[16:19], v4 offset:5120
	ds_read_b128 v[20:23], v4 offset:5136
	ds_read_b128 v[24:27], v4 offset:6144
	ds_read_b128 v[28:31], v4 offset:6160
	ds_read_b128 v[32:35], v4 offset:7168
	ds_read_b128 v[36:39], v4 offset:7184
	s_waitcnt lgkmcnt(0)
	v_cmp_ge_u32_e32 vcc, 4, v6
	v_cndmask_b32_e32 v8, 0, v8, vcc
	v_cndmask_b32_e32 v9, 0, v9, vcc
	v_cndmask_b32_e32 v10, 0, v10, vcc
	v_cndmask_b32_e32 v11, 0, v11, vcc
	v_cndmask_b32_e32 v12, 0, v12, vcc
	v_cndmask_b32_e32 v13, 0, v13, vcc
	v_cndmask_b32_e32 v14, 0, v14, vcc
	v_cndmask_b32_e32 v15, 0, v15, vcc
	v_cvt_pk_bf16_f32 v8, v8, v9
	v_cvt_pk_bf16_f32 v9, v10, v11
	v_cvt_pk_bf16_f32 v10, v12, v13
	v_cvt_pk_bf16_f32 v11, v14, v15
	global_store_dwordx4 v[2:3], v[8:11], off
	v_lshl_add_u64 v[2:3], v[2:3], 0, s[10:11]
	v_cmp_ge_u32_e32 vcc, 5, v6
	v_cndmask_b32_e32 v16, 0, v16, vcc
	v_cndmask_b32_e32 v17, 0, v17, vcc
	v_cndmask_b32_e32 v18, 0, v18, vcc
	v_cndmask_b32_e32 v19, 0, v19, vcc
	v_cndmask_b32_e32 v20, 0, v20, vcc
	v_cndmask_b32_e32 v21, 0, v21, vcc
	v_cndmask_b32_e32 v22, 0, v22, vcc
	v_cndmask_b32_e32 v23, 0, v23, vcc
	v_cvt_pk_bf16_f32 v16, v16, v17
	v_cvt_pk_bf16_f32 v17, v18, v19
	v_cvt_pk_bf16_f32 v18, v20, v21
	v_cvt_pk_bf16_f32 v19, v22, v23
	global_store_dwordx4 v[2:3], v[16:19], off
	v_lshl_add_u64 v[2:3], v[2:3], 0, s[10:11]
	v_cmp_ge_u32_e32 vcc, 6, v6
	v_cndmask_b32_e32 v24, 0, v24, vcc
	v_cndmask_b32_e32 v25, 0, v25, vcc
	v_cndmask_b32_e32 v26, 0, v26, vcc
	v_cndmask_b32_e32 v27, 0, v27, vcc
	v_cndmask_b32_e32 v28, 0, v28, vcc
	v_cndmask_b32_e32 v29, 0, v29, vcc
	v_cndmask_b32_e32 v30, 0, v30, vcc
	v_cndmask_b32_e32 v31, 0, v31, vcc
	v_cvt_pk_bf16_f32 v24, v24, v25
	v_cvt_pk_bf16_f32 v25, v26, v27
	v_cvt_pk_bf16_f32 v26, v28, v29
	v_cvt_pk_bf16_f32 v27, v30, v31
	global_store_dwordx4 v[2:3], v[24:27], off
	v_lshl_add_u64 v[2:3], v[2:3], 0, s[10:11]
	v_cmp_ge_u32_e32 vcc, 7, v6
	v_cndmask_b32_e32 v32, 0, v32, vcc
	v_cndmask_b32_e32 v33, 0, v33, vcc
	v_cndmask_b32_e32 v34, 0, v34, vcc
	v_cndmask_b32_e32 v35, 0, v35, vcc
	v_cndmask_b32_e32 v36, 0, v36, vcc
	v_cndmask_b32_e32 v37, 0, v37, vcc
	v_cndmask_b32_e32 v38, 0, v38, vcc
	v_cndmask_b32_e32 v39, 0, v39, vcc
	v_cvt_pk_bf16_f32 v32, v32, v33
	v_cvt_pk_bf16_f32 v33, v34, v35
	v_cvt_pk_bf16_f32 v34, v36, v37
	v_cvt_pk_bf16_f32 v35, v38, v39
	global_store_dwordx4 v[2:3], v[32:35], off
	v_lshl_add_u64 v[2:3], v[2:3], 0, s[10:11]
	ds_read_b128 v[8:11], v4 offset:8192
	ds_read_b128 v[12:15], v4 offset:8208
	ds_read_b128 v[16:19], v4 offset:9216
	ds_read_b128 v[20:23], v4 offset:9232
	ds_read_b128 v[24:27], v4 offset:10240
	ds_read_b128 v[28:31], v4 offset:10256
	ds_read_b128 v[32:35], v4 offset:11264
	ds_read_b128 v[36:39], v4 offset:11280
	s_waitcnt lgkmcnt(0)
	v_cmp_ge_u32_e32 vcc, 8, v6
	v_cndmask_b32_e32 v8, 0, v8, vcc
	v_cndmask_b32_e32 v9, 0, v9, vcc
	v_cndmask_b32_e32 v10, 0, v10, vcc
	v_cndmask_b32_e32 v11, 0, v11, vcc
	v_cndmask_b32_e32 v12, 0, v12, vcc
	v_cndmask_b32_e32 v13, 0, v13, vcc
	v_cndmask_b32_e32 v14, 0, v14, vcc
	v_cndmask_b32_e32 v15, 0, v15, vcc
	v_cvt_pk_bf16_f32 v8, v8, v9
	v_cvt_pk_bf16_f32 v9, v10, v11
	v_cvt_pk_bf16_f32 v10, v12, v13
	v_cvt_pk_bf16_f32 v11, v14, v15
	global_store_dwordx4 v[2:3], v[8:11], off
	v_lshl_add_u64 v[2:3], v[2:3], 0, s[10:11]
	v_cmp_ge_u32_e32 vcc, 9, v6
	v_cndmask_b32_e32 v16, 0, v16, vcc
	v_cndmask_b32_e32 v17, 0, v17, vcc
	v_cndmask_b32_e32 v18, 0, v18, vcc
	v_cndmask_b32_e32 v19, 0, v19, vcc
	v_cndmask_b32_e32 v20, 0, v20, vcc
	v_cndmask_b32_e32 v21, 0, v21, vcc
	v_cndmask_b32_e32 v22, 0, v22, vcc
	v_cndmask_b32_e32 v23, 0, v23, vcc
	v_cvt_pk_bf16_f32 v16, v16, v17
	v_cvt_pk_bf16_f32 v17, v18, v19
	v_cvt_pk_bf16_f32 v18, v20, v21
	v_cvt_pk_bf16_f32 v19, v22, v23
	global_store_dwordx4 v[2:3], v[16:19], off
	v_lshl_add_u64 v[2:3], v[2:3], 0, s[10:11]
	v_cmp_ge_u32_e32 vcc, 10, v6
	v_cndmask_b32_e32 v24, 0, v24, vcc
	v_cndmask_b32_e32 v25, 0, v25, vcc
	v_cndmask_b32_e32 v26, 0, v26, vcc
	v_cndmask_b32_e32 v27, 0, v27, vcc
	v_cndmask_b32_e32 v28, 0, v28, vcc
	v_cndmask_b32_e32 v29, 0, v29, vcc
	v_cndmask_b32_e32 v30, 0, v30, vcc
	v_cndmask_b32_e32 v31, 0, v31, vcc
	v_cvt_pk_bf16_f32 v24, v24, v25
	v_cvt_pk_bf16_f32 v25, v26, v27
	v_cvt_pk_bf16_f32 v26, v28, v29
	v_cvt_pk_bf16_f32 v27, v30, v31
	global_store_dwordx4 v[2:3], v[24:27], off
	v_lshl_add_u64 v[2:3], v[2:3], 0, s[10:11]
	v_cmp_ge_u32_e32 vcc, 11, v6
	v_cndmask_b32_e32 v32, 0, v32, vcc
	v_cndmask_b32_e32 v33, 0, v33, vcc
	v_cndmask_b32_e32 v34, 0, v34, vcc
	v_cndmask_b32_e32 v35, 0, v35, vcc
	v_cndmask_b32_e32 v36, 0, v36, vcc
	v_cndmask_b32_e32 v37, 0, v37, vcc
	v_cndmask_b32_e32 v38, 0, v38, vcc
	v_cndmask_b32_e32 v39, 0, v39, vcc
	v_cvt_pk_bf16_f32 v32, v32, v33
	v_cvt_pk_bf16_f32 v33, v34, v35
	v_cvt_pk_bf16_f32 v34, v36, v37
	v_cvt_pk_bf16_f32 v35, v38, v39
	global_store_dwordx4 v[2:3], v[32:35], off
	v_lshl_add_u64 v[2:3], v[2:3], 0, s[10:11]
	ds_read_b128 v[8:11], v4 offset:12288
	ds_read_b128 v[12:15], v4 offset:12304
	ds_read_b128 v[16:19], v4 offset:13312
	ds_read_b128 v[20:23], v4 offset:13328
	ds_read_b128 v[24:27], v4 offset:14336
	ds_read_b128 v[28:31], v4 offset:14352
	ds_read_b128 v[32:35], v4 offset:15360
	ds_read_b128 v[36:39], v4 offset:15376
	s_waitcnt lgkmcnt(0)
	v_cmp_ge_u32_e32 vcc, 12, v6
	v_cndmask_b32_e32 v8, 0, v8, vcc
	v_cndmask_b32_e32 v9, 0, v9, vcc
	v_cndmask_b32_e32 v10, 0, v10, vcc
	v_cndmask_b32_e32 v11, 0, v11, vcc
	v_cndmask_b32_e32 v12, 0, v12, vcc
	v_cndmask_b32_e32 v13, 0, v13, vcc
	v_cndmask_b32_e32 v14, 0, v14, vcc
	v_cndmask_b32_e32 v15, 0, v15, vcc
	v_cvt_pk_bf16_f32 v8, v8, v9
	v_cvt_pk_bf16_f32 v9, v10, v11
	v_cvt_pk_bf16_f32 v10, v12, v13
	v_cvt_pk_bf16_f32 v11, v14, v15
	global_store_dwordx4 v[2:3], v[8:11], off
	v_lshl_add_u64 v[2:3], v[2:3], 0, s[10:11]
	v_cmp_ge_u32_e32 vcc, 13, v6
	v_cndmask_b32_e32 v16, 0, v16, vcc
	v_cndmask_b32_e32 v17, 0, v17, vcc
	v_cndmask_b32_e32 v18, 0, v18, vcc
	v_cndmask_b32_e32 v19, 0, v19, vcc
	v_cndmask_b32_e32 v20, 0, v20, vcc
	v_cndmask_b32_e32 v21, 0, v21, vcc
	v_cndmask_b32_e32 v22, 0, v22, vcc
	v_cndmask_b32_e32 v23, 0, v23, vcc
	v_cvt_pk_bf16_f32 v16, v16, v17
	v_cvt_pk_bf16_f32 v17, v18, v19
	v_cvt_pk_bf16_f32 v18, v20, v21
	v_cvt_pk_bf16_f32 v19, v22, v23
	global_store_dwordx4 v[2:3], v[16:19], off
	v_lshl_add_u64 v[2:3], v[2:3], 0, s[10:11]
	v_cmp_ge_u32_e32 vcc, 14, v6
	v_cndmask_b32_e32 v24, 0, v24, vcc
	v_cndmask_b32_e32 v25, 0, v25, vcc
	v_cndmask_b32_e32 v26, 0, v26, vcc
	v_cndmask_b32_e32 v27, 0, v27, vcc
	v_cndmask_b32_e32 v28, 0, v28, vcc
	v_cndmask_b32_e32 v29, 0, v29, vcc
	v_cndmask_b32_e32 v30, 0, v30, vcc
	v_cndmask_b32_e32 v31, 0, v31, vcc
	v_cvt_pk_bf16_f32 v24, v24, v25
	v_cvt_pk_bf16_f32 v25, v26, v27
	v_cvt_pk_bf16_f32 v26, v28, v29
	v_cvt_pk_bf16_f32 v27, v30, v31
	global_store_dwordx4 v[2:3], v[24:27], off
	v_lshl_add_u64 v[2:3], v[2:3], 0, s[10:11]
	v_cmp_ge_u32_e32 vcc, 15, v6
	v_cndmask_b32_e32 v32, 0, v32, vcc
	v_cndmask_b32_e32 v33, 0, v33, vcc
	v_cndmask_b32_e32 v34, 0, v34, vcc
	v_cndmask_b32_e32 v35, 0, v35, vcc
	v_cndmask_b32_e32 v36, 0, v36, vcc
	v_cndmask_b32_e32 v37, 0, v37, vcc
	v_cndmask_b32_e32 v38, 0, v38, vcc
	v_cndmask_b32_e32 v39, 0, v39, vcc
	v_cvt_pk_bf16_f32 v32, v32, v33
	v_cvt_pk_bf16_f32 v33, v34, v35
	v_cvt_pk_bf16_f32 v34, v36, v37
	v_cvt_pk_bf16_f32 v35, v38, v39
	global_store_dwordx4 v[2:3], v[32:35], off
	v_lshl_add_u64 v[2:3], v[2:3], 0, s[10:11]
	v_lshrrev_b32_e32 v1, 4, v136
	v_and_b32_e32 v7, 15, v136
	v_and_b32_e32 v6, 7, v7
	v_lshlrev_b32_e32 v6, 5, v6
	v_and_b32_e32 v5, 15, v1
	v_lshl_add_u32 v5, v5, 8, v6
	ds_read_b128 v[8:11], v5 offset:16896
	ds_read_b128 v[12:15], v5 offset:16912
	ds_read_b128 v[16:19], v5 offset:20992
	ds_read_b128 v[20:23], v5 offset:21008
	v_lshrrev_b32_e32 v4, 4, v1
	v_lshl_add_u32 v4, v4, 8, v6
	v_add_u32_e32 v5, 4352, v4
	v_cmp_lt_u32_e32 vcc, 7, v7
	v_cndmask_b32_e32 v6, v4, v5, vcc
	v_cndmask_b32_e32 v5, v5, v4, vcc
	v_mul_u32_u24_e32 v2, 0x300, v1
	v_lshl_add_u32 v2, v7, 4, v2
	v_add_u32_e32 v2, 0x200, v2
	v_mov_b32_e32 v3, 0
	v_lshl_add_u64 v[2:3], s[4:5], 0, v[2:3]
	s_mov_b32 s10, 0x6000
	s_waitcnt lgkmcnt(0)
	v_cndmask_b32_e64 v8, v8, -v8, vcc
	v_cndmask_b32_e64 v9, v9, -v9, vcc
	v_cndmask_b32_e64 v10, v10, -v10, vcc
	v_cndmask_b32_e64 v11, v11, -v11, vcc
	v_cndmask_b32_e64 v12, v12, -v12, vcc
	v_cndmask_b32_e64 v13, v13, -v13, vcc
	v_cndmask_b32_e64 v14, v14, -v14, vcc
	v_cndmask_b32_e64 v15, v15, -v15, vcc
	ds_read_b128 v[24:27], v6 offset:256
	ds_read_b128 v[28:31], v6 offset:272
	ds_read_b128 v[32:35], v5 offset:256
	ds_read_b128 v[36:39], v5 offset:272
	s_waitcnt lgkmcnt(0)
	v_mul_f32_e32 v32, v16, v32
	v_fma_f32 v24, v8, v24, -v32
	v_mul_f32_e32 v33, v17, v33
	v_fma_f32 v25, v9, v25, -v33
	v_mul_f32_e32 v34, v18, v34
	v_fma_f32 v26, v10, v26, -v34
	v_mul_f32_e32 v35, v19, v35
	v_fma_f32 v27, v11, v27, -v35
	v_mul_f32_e32 v36, v20, v36
	v_fma_f32 v28, v12, v28, -v36
	v_mul_f32_e32 v37, v21, v37
	v_fma_f32 v29, v13, v29, -v37
	v_mul_f32_e32 v38, v22, v38
	v_fma_f32 v30, v14, v30, -v38
	v_mul_f32_e32 v39, v23, v39
	v_fma_f32 v31, v15, v31, -v39
	v_cvt_pk_bf16_f32 v24, v24, v25
	v_cvt_pk_bf16_f32 v25, v26, v27
	v_cvt_pk_bf16_f32 v26, v28, v29
	v_cvt_pk_bf16_f32 v27, v30, v31
	global_store_dwordx4 v[2:3], v[24:27], off
	v_lshl_add_u64 v[2:3], v[2:3], 0, s[10:11]
	ds_read_b128 v[24:27], v6 offset:768
	ds_read_b128 v[28:31], v6 offset:784
	ds_read_b128 v[32:35], v5 offset:768
	ds_read_b128 v[36:39], v5 offset:784
	s_waitcnt lgkmcnt(0)
	v_mul_f32_e32 v32, v16, v32
	v_fma_f32 v24, v8, v24, -v32
	v_mul_f32_e32 v33, v17, v33
	v_fma_f32 v25, v9, v25, -v33
	v_mul_f32_e32 v34, v18, v34
	v_fma_f32 v26, v10, v26, -v34
	v_mul_f32_e32 v35, v19, v35
	v_fma_f32 v27, v11, v27, -v35
	v_mul_f32_e32 v36, v20, v36
	v_fma_f32 v28, v12, v28, -v36
	v_mul_f32_e32 v37, v21, v37
	v_fma_f32 v29, v13, v29, -v37
	v_mul_f32_e32 v38, v22, v38
	v_fma_f32 v30, v14, v30, -v38
	v_mul_f32_e32 v39, v23, v39
	v_fma_f32 v31, v15, v31, -v39
	v_cvt_pk_bf16_f32 v24, v24, v25
	v_cvt_pk_bf16_f32 v25, v26, v27
	v_cvt_pk_bf16_f32 v26, v28, v29
	v_cvt_pk_bf16_f32 v27, v30, v31
	global_store_dwordx4 v[2:3], v[24:27], off
	v_lshl_add_u64 v[2:3], v[2:3], 0, s[10:11]
	ds_read_b128 v[24:27], v6 offset:1280
	ds_read_b128 v[28:31], v6 offset:1296
	ds_read_b128 v[32:35], v5 offset:1280
	ds_read_b128 v[36:39], v5 offset:1296
	s_waitcnt lgkmcnt(0)
	v_mul_f32_e32 v32, v16, v32
	v_fma_f32 v24, v8, v24, -v32
	v_mul_f32_e32 v33, v17, v33
	v_fma_f32 v25, v9, v25, -v33
	v_mul_f32_e32 v34, v18, v34
	v_fma_f32 v26, v10, v26, -v34
	v_mul_f32_e32 v35, v19, v35
	v_fma_f32 v27, v11, v27, -v35
	v_mul_f32_e32 v36, v20, v36
	v_fma_f32 v28, v12, v28, -v36
	v_mul_f32_e32 v37, v21, v37
	v_fma_f32 v29, v13, v29, -v37
	v_mul_f32_e32 v38, v22, v38
	v_fma_f32 v30, v14, v30, -v38
	v_mul_f32_e32 v39, v23, v39
	v_fma_f32 v31, v15, v31, -v39
	v_cvt_pk_bf16_f32 v24, v24, v25
	v_cvt_pk_bf16_f32 v25, v26, v27
	v_cvt_pk_bf16_f32 v26, v28, v29
	v_cvt_pk_bf16_f32 v27, v30, v31
	global_store_dwordx4 v[2:3], v[24:27], off
	v_lshl_add_u64 v[2:3], v[2:3], 0, s[10:11]
	ds_read_b128 v[24:27], v6 offset:1792
	ds_read_b128 v[28:31], v6 offset:1808
	ds_read_b128 v[32:35], v5 offset:1792
	ds_read_b128 v[36:39], v5 offset:1808
	s_waitcnt lgkmcnt(0)
	v_mul_f32_e32 v32, v16, v32
	v_fma_f32 v24, v8, v24, -v32
	v_mul_f32_e32 v33, v17, v33
	v_fma_f32 v25, v9, v25, -v33
	v_mul_f32_e32 v34, v18, v34
	v_fma_f32 v26, v10, v26, -v34
	v_mul_f32_e32 v35, v19, v35
	v_fma_f32 v27, v11, v27, -v35
	v_mul_f32_e32 v36, v20, v36
	v_fma_f32 v28, v12, v28, -v36
	v_mul_f32_e32 v37, v21, v37
	v_fma_f32 v29, v13, v29, -v37
	v_mul_f32_e32 v38, v22, v38
	v_fma_f32 v30, v14, v30, -v38
	v_mul_f32_e32 v39, v23, v39
	v_fma_f32 v31, v15, v31, -v39
	v_cvt_pk_bf16_f32 v24, v24, v25
	v_cvt_pk_bf16_f32 v25, v26, v27
	v_cvt_pk_bf16_f32 v26, v28, v29
	v_cvt_pk_bf16_f32 v27, v30, v31
	global_store_dwordx4 v[2:3], v[24:27], off
	v_lshl_add_u64 v[2:3], v[2:3], 0, s[10:11]
	ds_read_b128 v[24:27], v6 offset:2304
	ds_read_b128 v[28:31], v6 offset:2320
	ds_read_b128 v[32:35], v5 offset:2304
	ds_read_b128 v[36:39], v5 offset:2320
	s_waitcnt lgkmcnt(0)
	v_mul_f32_e32 v32, v16, v32
	v_fma_f32 v24, v8, v24, -v32
	v_mul_f32_e32 v33, v17, v33
	v_fma_f32 v25, v9, v25, -v33
	v_mul_f32_e32 v34, v18, v34
	v_fma_f32 v26, v10, v26, -v34
	v_mul_f32_e32 v35, v19, v35
	v_fma_f32 v27, v11, v27, -v35
	v_mul_f32_e32 v36, v20, v36
	v_fma_f32 v28, v12, v28, -v36
	v_mul_f32_e32 v37, v21, v37
	v_fma_f32 v29, v13, v29, -v37
	v_mul_f32_e32 v38, v22, v38
	v_fma_f32 v30, v14, v30, -v38
	v_mul_f32_e32 v39, v23, v39
	v_fma_f32 v31, v15, v31, -v39
	v_cvt_pk_bf16_f32 v24, v24, v25
	v_cvt_pk_bf16_f32 v25, v26, v27
	v_cvt_pk_bf16_f32 v26, v28, v29
	v_cvt_pk_bf16_f32 v27, v30, v31
	global_store_dwordx4 v[2:3], v[24:27], off
	v_lshl_add_u64 v[2:3], v[2:3], 0, s[10:11]
	ds_read_b128 v[24:27], v6 offset:2816
	ds_read_b128 v[28:31], v6 offset:2832
	ds_read_b128 v[32:35], v5 offset:2816
	ds_read_b128 v[36:39], v5 offset:2832
	s_waitcnt lgkmcnt(0)
	v_mul_f32_e32 v32, v16, v32
	v_fma_f32 v24, v8, v24, -v32
	v_mul_f32_e32 v33, v17, v33
	v_fma_f32 v25, v9, v25, -v33
	v_mul_f32_e32 v34, v18, v34
	v_fma_f32 v26, v10, v26, -v34
	v_mul_f32_e32 v35, v19, v35
	v_fma_f32 v27, v11, v27, -v35
	v_mul_f32_e32 v36, v20, v36
	v_fma_f32 v28, v12, v28, -v36
	v_mul_f32_e32 v37, v21, v37
	v_fma_f32 v29, v13, v29, -v37
	v_mul_f32_e32 v38, v22, v38
	v_fma_f32 v30, v14, v30, -v38
	v_mul_f32_e32 v39, v23, v39
	v_fma_f32 v31, v15, v31, -v39
	v_cvt_pk_bf16_f32 v24, v24, v25
	v_cvt_pk_bf16_f32 v25, v26, v27
	v_cvt_pk_bf16_f32 v26, v28, v29
	v_cvt_pk_bf16_f32 v27, v30, v31
	global_store_dwordx4 v[2:3], v[24:27], off
	v_lshl_add_u64 v[2:3], v[2:3], 0, s[10:11]
	ds_read_b128 v[24:27], v6 offset:3328
	ds_read_b128 v[28:31], v6 offset:3344
	ds_read_b128 v[32:35], v5 offset:3328
	ds_read_b128 v[36:39], v5 offset:3344
	s_waitcnt lgkmcnt(0)
	v_mul_f32_e32 v32, v16, v32
	v_fma_f32 v24, v8, v24, -v32
	v_mul_f32_e32 v33, v17, v33
	v_fma_f32 v25, v9, v25, -v33
	v_mul_f32_e32 v34, v18, v34
	v_fma_f32 v26, v10, v26, -v34
	v_mul_f32_e32 v35, v19, v35
	v_fma_f32 v27, v11, v27, -v35
	v_mul_f32_e32 v36, v20, v36
	v_fma_f32 v28, v12, v28, -v36
	v_mul_f32_e32 v37, v21, v37
	v_fma_f32 v29, v13, v29, -v37
	v_mul_f32_e32 v38, v22, v38
	v_fma_f32 v30, v14, v30, -v38
	v_mul_f32_e32 v39, v23, v39
	v_fma_f32 v31, v15, v31, -v39
	v_cvt_pk_bf16_f32 v24, v24, v25
	v_cvt_pk_bf16_f32 v25, v26, v27
	v_cvt_pk_bf16_f32 v26, v28, v29
	v_cvt_pk_bf16_f32 v27, v30, v31
	global_store_dwordx4 v[2:3], v[24:27], off
	v_lshl_add_u64 v[2:3], v[2:3], 0, s[10:11]
	ds_read_b128 v[24:27], v6 offset:3840
	ds_read_b128 v[28:31], v6 offset:3856
	ds_read_b128 v[32:35], v5 offset:3840
	ds_read_b128 v[36:39], v5 offset:3856
	s_waitcnt lgkmcnt(0)
	v_mul_f32_e32 v32, v16, v32
	v_fma_f32 v24, v8, v24, -v32
	v_mul_f32_e32 v33, v17, v33
	v_fma_f32 v25, v9, v25, -v33
	v_mul_f32_e32 v34, v18, v34
	v_fma_f32 v26, v10, v26, -v34
	v_mul_f32_e32 v35, v19, v35
	v_fma_f32 v27, v11, v27, -v35
	v_mul_f32_e32 v36, v20, v36
	v_fma_f32 v28, v12, v28, -v36
	v_mul_f32_e32 v37, v21, v37
	v_fma_f32 v29, v13, v29, -v37
	v_mul_f32_e32 v38, v22, v38
	v_fma_f32 v30, v14, v30, -v38
	v_mul_f32_e32 v39, v23, v39
	v_fma_f32 v31, v15, v31, -v39
	v_cvt_pk_bf16_f32 v24, v24, v25
	v_cvt_pk_bf16_f32 v25, v26, v27
	v_cvt_pk_bf16_f32 v26, v28, v29
	v_cvt_pk_bf16_f32 v27, v30, v31
	global_store_dwordx4 v[2:3], v[24:27], off
	v_lshl_add_u64 v[2:3], v[2:3], 0, s[10:11]
